# norm phases: context-GEMM workgroups skip the dynamic norm queue afterwards
# speedup vs baseline: 1.0155x; 1.0027x over previous
;     ...
;         OneUnit S; S.u.pm = bid & 3; S.u.pn = bid >> 2; S.valid = bid < 32;
;         EpiQKV E; E.qkv = p.QKV; E.qkn = p.qk_norm + cl * 6 * 64; E.rope = p.rope; E.rowbase = TLAT;
;         gemm_phase(lds, Gemm{p.H + (size_t)TLAT * LDK, p.wt_in + (size_t)cl * INW * LDK, DM}, S, E);
;       }
;       norm_dyn(p, layer, 0, 0, TLAT, &p.counters[32 + g + coff]);
.LBB0_194:
	s_barrier
	s_branch .LBB0_203

;     ...
;       if (hasc) {
;         OneUnit S; S.u.pm = bid & 3; S.u.pn = bid >> 2; S.valid = bid < 88;
;         EpiGU E; E.act = p.ACT + (size_t)TLAT * LDF;
;         gemm_phase(lds, Gemm{p.H + (size_t)TLAT * LDK, p.wt_gu + (size_t)cl * GUW * LDK, DM}, S, E);
;       }
;       norm_dyn(p, layer, 1, 0, TLAT, &p.counters[32 + g + coff]);
.LBB0_875:
	s_barrier
	v_readlane_b32 s12, v252, 19
	v_readlane_b32 s13, v252, 20
	v_readlane_b32 s14, v252, 21
	v_readlane_b32 s15, v252, 22
	v_readlane_b32 s16, v252, 23
	v_readlane_b32 s17, v252, 24
	v_readlane_b32 s18, v252, 25
	v_readlane_b32 s19, v252, 26
	v_readlane_b32 s20, v252, 27
	v_readlane_b32 s21, v252, 28
	v_readlane_b32 s22, v252, 29
	v_readlane_b32 s23, v252, 30
	v_readlane_b32 s24, v252, 31
	v_readlane_b32 s25, v252, 32
	v_readlane_b32 s26, v252, 33
	v_readlane_b32 s27, v252, 34
	s_branch .LBB0_884
